# phases 6 and 8(layer 0): half of the workgroups (blockIdx bit 3) run the weight-prep section before the GEMM section (re-running the phase preamble in between) so HBM-bound prep overlaps the other hal
# baseline (speedup 1.0000x reference)
; #define LAS __attribute__((address_space(3)))
; __device__ __forceinline__ unsigned xb_add(unsigned* p, unsigned v) { return __hip_atomic_fetch_add(p, v, __ATOMIC_RELAXED, __HIP_MEMORY_SCOPE_AGENT); }
; __device__ __forceinline__ unsigned xb_xcc_id() { return (unsigned)__builtin_amdgcn_s_getreg((3 << 11) | 20) & 0xFu; }
; __device__ __forceinline__ XcdBarrier xcd_barrier_post(unsigned* bar, volatile LAS unsigned* st) {
;     XcdBarrier b; b.bar = bar; b.x = xb_xcc_id(); b.st = st;
;     if (threadIdx.x == 0) (void)xb_add(&bar[XB_XCNT(b.x)], 1u);
;     return b;
; __global__ void __launch_bounds__(512, 2) mega_fwd(Params p_) {
;     extern __shared__ __attribute__((aligned(16))) unsigned char lds_raw[];
;     LAS unsigned char* lds = (LAS unsigned char*)lds_raw;
;     cg::grid_group grid = cg::this_grid();
;     const int ph_lo = p_.ph_lo, ph_hi = p_.ph_hi;
;     volatile LAS unsigned* bst = (volatile LAS unsigned*)(lds + STAGE_BYTES);
;     if (threadIdx.x < 4) bst[threadIdx.x] = 0u;
;     __syncthreads();
;     const XcdBarrier xbar = xcd_barrier_post((unsigned*)(p_.ws + WS_BAR), bst);
_Z8mega_fwd6Params:
	s_mov_b64 s[70:71], s[0:1]
	s_mov_b32 s98, 0
	s_load_dwordx4 s[24:27], s[0:1], 0xa8
	s_nop 0
	s_load_dwordx2 s[0:1], s[70:71], 0xb8
	v_and_b32_e32 v176, 0x3ff, v0
	s_mov_b32 s53, s2
	v_cmp_gt_u32_e32 vcc, 4, v176
	s_waitcnt lgkmcnt(0)
	v_writelane_b32 v240, s0, 0
	s_nop 1
	v_writelane_b32 v240, s1, 1
	s_add_u32 s0, s70, 0xb8
	s_addc_u32 s1, s71, 0
	v_writelane_b32 v240, s0, 2
	s_nop 1
	v_writelane_b32 v240, s1, 3
	s_and_saveexec_b64 s[0:1], vcc
	v_lshl_add_u32 v1, v176, 2, 0
	v_add_u32_e32 v1, 0x20000, v1
	v_mov_b32_e32 v2, 0
	ds_write_b32 v1, v2
	s_or_b64 exec, exec, s[0:1]
	s_waitcnt lgkmcnt(0)
	s_barrier
	s_add_u32 s0, s24, 0x4280000
	s_getreg_b32 s2, hwreg(HW_REG_XCC_ID, 0, 4)
	s_addc_u32 s1, s25, 0
	s_and_b32 s2, s2, 15
	v_cmp_eq_u32_e64 s[6:7], 0, v176
	s_mov_b64 s[4:5], exec
	s_nop 0
	v_writelane_b32 v240, s6, 4
	s_nop 1
	v_writelane_b32 v240, s7, 5
	s_and_b64 s[6:7], s[4:5], s[6:7]
	s_mov_b64 exec, s[6:7]
	s_cbranch_execz .LBB0_5
	s_mov_b64 s[6:7], exec
	v_mbcnt_lo_u32_b32 v1, s6, 0
	v_mbcnt_hi_u32_b32 v1, s7, v1
	v_cmp_eq_u32_e32 vcc, 0, v1
	s_and_b64 s[8:9], exec, vcc
	s_mov_b64 exec, s[8:9]
	s_cbranch_execz .LBB0_5
	s_lshl_b32 s3, s2, 8
	s_bcnt1_i32_b64 s6, s[6:7]
	v_mov_b32_e32 v1, s3
	v_mov_b32_e32 v2, s6
	global_atomic_add v1, v2, s[0:1] offset:1024

; #define LAS __attribute__((address_space(3)))
; __global__ void __launch_bounds__(512, 2) mega_fwd(Params p_) {
;     ...
;     for (int ph = ph_lo; ph < ph_hi; ++ph) {
;         if (ph > ph_lo) { if (ph_hi > 4096) grid.sync(); else xcd_barrier(xbar); }
;         CParams* pp = (CParams*)__builtin_amdgcn_kernarg_segment_ptr(); asm volatile("" : "+s"(pp));
;         int tid_ = threadIdx.x; asm volatile("" : "+v"(tid_));
;         const int tid = tid_, wave = __builtin_amdgcn_readfirstlane(tid >> 6), lane = tid & 63;
;         const int G = gridDim.x, c = blockIdx.x, gw = c * 8 + wave, NGW = G * 8;
;         unsigned char* ws = pp->ws; float* outp = pp->out;
;         bf16_t* WinT = (bf16_t*)(ws + WS_WIN); bf16_t* WgluT = (bf16_t*)(ws + WS_WGLU); bf16_t* WoutT = (bf16_t*)(ws + WS_WOUT);
;         bf16_t* WguT = (bf16_t*)(ws + WS_WGU); bf16_t* WdT = (bf16_t*)(ws + WS_WD);
;         float* ropec = (float*)(ws + WS_ROPE); float* ropes = ropec + SEQ * 128; float* ysq = (float*)(ws + WS_YSQ); float* rsa = (float*)(ws + WS_RSA); float* rsb = (float*)(ws + WS_RSB);
;         bf16_t* Qb = (bf16_t*)(ws + WS_Q); bf16_t* Kb = (bf16_t*)(ws + WS_K); bf16_t* Yb = (bf16_t*)(ws + WS_Y); bf16_t* Vt = (bf16_t*)(ws + WS_VT);
;         bf16_t* Gb = (bf16_t*)(ws + WS_G); bf16_t* Ub = (bf16_t*)(ws + WS_U); bf16_t* GRb = (bf16_t*)(ws + WS_GR); bf16_t* GSb = (bf16_t*)(ws + WS_GS);
;         bf16_t* Pb = (bf16_t*)(ws + WS_P); bf16_t* Hb = (bf16_t*)(ws + WS_H); bf16_t* Mg = (bf16_t*)(ws + WS_MERGED); bf16_t* Hm = (bf16_t*)(ws + WS_HMID);
;         LAS float* scr = (LAS float*)(lds + wave * 16384);
;         const int layer = ph >= PER_LAYER ? 1 : 0, sub = ph >= PER_LAYER ? ph - PER_LAYER + 1 : ph;
;         if (ph == 2 * PER_LAYER - 1) { norm_rows_final(outp, pp->in[19], rsa, gw, NGW, lane); continue; }
;         const float* xcur = (layer == 0) ? pp->in[0] : outp;
;         switch (sub) {
;     ...
;         case 8: {
;             GemmD g{}; g.A = Hm; g.Bt = WdT; g.lda = DFF; g.ldb = DFF; g.K = DFF; g.nM = 64; g.nN = 8; g.nZ = 1; g.zdiv = 1;
;             EpiRes E{outp, outp, layer == 1 ? (bf16_t*)nullptr : (bf16_t*)(ws + WS_XBM), rsa, (LAS float*)(lds + RED_OFF)}; gemm_phase(lds, g, E, G, c);
;             if (layer == 0) { prep_a(pp, 1, scr, gw, NGW, lane, c * 512 + tid, G * 512); __syncthreads(); }
.LBB0_84:
	s_mov_b32 s99, 0
	s_add_u32 s4, s58, 0x3000000
	s_addc_u32 s5, s59, 0
	v_writelane_b32 v238, s4, 53
	s_nop 1
	v_writelane_b32 v238, s5, 54
	s_add_u32 s4, s58, 0x3800000
	s_addc_u32 s5, s59, 0
	s_add_u32 s74, s58, 0xc300000
	s_addc_u32 s75, s59, 0
	s_add_u32 s24, s58, 0x4200000
	v_writelane_b32 v238, s4, 55
	s_addc_u32 s25, s59, 0
	s_nop 0
	v_writelane_b32 v238, s5, 56
	s_add_u32 s4, s58, 0x4250000
	s_addc_u32 s5, s59, 0
	s_add_u32 s76, s58, 0x4300000
	s_addc_u32 s77, s59, 0
	s_add_u32 s40, s58, 0x8300000
	s_addc_u32 s41, s59, 0
	s_add_u32 s14, s58, 0x1c300000
	v_writelane_b32 v238, s4, 57
	s_addc_u32 s15, s59, 0
	s_lshl_b32 s2, s2, 14
	v_writelane_b32 v238, s5, 58
	s_add_i32 s2, s2, 0
	v_writelane_b32 v238, s2, 59
	s_add_i32 s2, s8, -8
	s_and_b64 s[4:5], exec, s[78:79]
	s_cselect_b32 s2, s2, s8
	s_cmp_lt_i32 s2, 4
	s_mov_b64 s[4:5], -1
	v_writelane_b32 v238, s2, 60
	s_cbranch_scc1 .LBB0_309
	v_readlane_b32 s2, v238, 60
	s_cmp_lt_i32 s2, 6
	s_cbranch_scc1 .LBB0_256
	s_add_u32 s60, s58, 0xef00000
	s_addc_u32 s61, s59, 0
	v_readlane_b32 s2, v238, 60
	s_cmp_lt_i32 s2, 7
	s_cbranch_scc1 .LBB0_210
	s_add_u32 s62, s58, 0x20300000
	s_addc_u32 s63, s59, 0
	v_readlane_b32 s2, v238, 60
	s_cmp_lt_i32 s2, 8
	s_cbranch_scc1 .LBB0_192
	v_readlane_b32 s2, v238, 60
	s_cmp_eq_u32 s2, 8
	s_cbranch_scc0 .LBB0_191
	v_readlane_b32 s4, v240, 59
	v_mov_b32_e32 v0, v176
	v_readlane_b32 s5, v240, 60
	s_andn2_b64 vcc, exec, s[4:5]
	v_readfirstlane_b32 s19, v0
	s_cmp_eq_u32 s98, 2
	s_cbranch_scc1 .Lsw8_second
	s_cmp_lt_i32 s8, 9
	s_cbranch_scc0 .Lsw8_normal
	s_bitcmp1_b32 s53, 3
	s_cbranch_scc0 .Lsw8_normal
	s_mov_b32 s98, 1
	s_branch .LBB0_149
.Lsw8_second:
	s_cbranch_vccz .Lsw8_gemm
	s_mov_b32 s98, 0
	s_branch .LBB0_191
.Lsw8_normal:
	s_cbranch_vccnz .LBB0_149
.Lsw8_gemm:
	v_lshlrev_b32_e32 v1, 4, v0
	v_add_u32_e32 v2, 0x2000, v1
	v_ashrrev_i32_e32 v3, 31, v2
	v_lshrrev_b32_e32 v3, 22, v3
	v_add_u32_e32 v3, v2, v3
	v_ashrrev_i32_e32 v142, 10, v3
	v_mul_i32_i24_e32 v3, 0x400, v142
	v_sub_u32_e32 v2, v2, v3
	v_lshrrev_b32_e32 v3, 4, v2
	v_bitop3_b32 v2, v3, v2, 32 bitop3:0x6c
	v_ashrrev_i32_e32 v3, 31, v2
	v_lshrrev_b32_e32 v3, 26, v3
	v_add_u32_e32 v3, v2, v3
	v_lshlrev_b32_e32 v4, 3, v142
	v_ashrrev_i32_e32 v144, 6, v3
	v_and_b32_e32 v4, -16, v4
	v_add_u32_e32 v4, v144, v4
	v_and_b32_e32 v5, 3, v144
	s_mov_b32 s6, 0x7fffe0
	v_lshrrev_b32_e32 v6, 2, v4
	v_lshlrev_b32_e32 v7, 1, v4
	v_and_b32_e32 v3, 0xc0, v3
	v_and_or_b32 v5, v4, s6, v5
	v_and_b32_e32 v6, 4, v6
	v_and_b32_e32 v7, 24, v7
	v_sub_u32_e32 v2, v2, v3
	v_or3_b32 v5, v5, v6, v7
	v_lshlrev_b32_e32 v6, 5, v142
	v_ashrrev_i16_sdwa v2, v200, sext(v2) dst_sel:DWORD dst_unused:UNUSED_PAD src0_sel:DWORD src1_sel:BYTE_0
	v_and_b32_e32 v147, 32, v6
	v_bfe_i32 v151, v2, 0, 16
	s_movk_i32 s9, 0x1600
	v_mul_u32_u24_e32 v5, 0x1600, v5
	v_add_u32_e32 v2, v147, v151
	v_mul_lo_u32 v3, v4, s9
	v_add_lshl_u32 v128, v5, v2, 1
	v_add_lshl_u32 v130, v2, v3, 1
	v_bfe_i32 v2, v0, 27, 1
	v_lshrrev_b32_e32 v2, 22, v2
	v_add_u32_e32 v2, v1, v2
	v_and_b32_e32 v2, 0xfffffc00, v2
	v_sub_u32_e32 v1, v1, v2
	v_lshrrev_b32_e32 v2, 4, v1
	v_ashrrev_i32_e32 v3, 31, v0
	v_bitop3_b32 v1, v2, v1, 32 bitop3:0x6c
	v_lshrrev_b32_e32 v3, 26, v3
	v_bfe_u32 v145, v0, 4, 2
	v_and_b32_e32 v146, 15, v0
	v_ashrrev_i32_e32 v2, 31, v1
	v_add_u32_e32 v0, v0, v3
	v_lshrrev_b32_e32 v2, 26, v2
	v_ashrrev_i32_e32 v153, 6, v0
	v_add_u32_e32 v2, v1, v2
	v_lshlrev_b32_e32 v0, 3, v153
	v_ashrrev_i32_e32 v152, 6, v2
	v_and_b32_e32 v0, -16, v0
	v_add_u32_e32 v0, v152, v0
	v_and_b32_e32 v3, 3, v152
	v_lshrrev_b32_e32 v4, 2, v0
	v_lshlrev_b32_e32 v5, 1, v0
	v_and_b32_e32 v2, 0xc0, v2
	v_and_or_b32 v3, v0, s6, v3
	v_and_b32_e32 v4, 4, v4
	v_and_b32_e32 v5, 24, v5
	v_sub_u32_e32 v1, v1, v2
	s_ashr_i32 s22, s19, 8
	v_or3_b32 v3, v3, v4, v5
	v_lshlrev_b32_e32 v4, 5, v153
	v_ashrrev_i16_sdwa v1, v200, sext(v1) dst_sel:DWORD dst_unused:UNUSED_PAD src0_sel:DWORD src1_sel:BYTE_0
	s_ashr_i32 s2, s19, 6
	s_lshl_b32 s23, s22, 6
	v_and_b32_e32 v154, 32, v4
	v_bfe_i32 v155, v1, 0, 16
	v_readlane_b32 s6, v239, 21
	s_and_b32 s4, s2, 3
	v_add_u32_e32 v1, v154, v155
	v_mul_lo_u32 v0, v0, s9
	s_add_i32 s6, s6, s23
	s_lshl_b32 s5, s4, 5
	v_add_lshl_u32 v132, v1, v0, 1
	v_or_b32_e32 v0, s6, v146
	v_readlane_b32 s6, v239, 23
	v_lshlrev_b32_e32 v143, 3, v145
	v_mul_u32_u24_e32 v3, 0x1600, v3
	s_or_b32 s6, s6, s5
	v_or_b32_e32 v6, 16, v0
	v_add_lshl_u32 v178, v3, v1, 1
	v_or_b32_e32 v2, s6, v143
	v_ashrrev_i32_e32 v1, 31, v0
; #define PG8_STAGE(bufoff, gbase, voff) do { _Pragma("unroll") for (int _i = 0; _i < 2; ++_i) \
;         __builtin_amdgcn_global_load_lds((const unsigned*)((const char*)(gbase) + (voff)[_i]), (LAS unsigned*)(lds + (bufoff) + ldsw + _i * 8192), 16, 0, 0); } while (0)
; #define PG8_WAIT_V(n) asm volatile("s_waitcnt vmcnt(" #n ")" ::: "memory")
; #define PG8_BAR __builtin_amdgcn_s_barrier()
; template <class Epi>
; __device__ __forceinline__ void gemm_phase(LAS unsigned char* lds, const GemmD g, const Epi& E, int G, int c) {
;     ...
;     const char* cA = PG8_APTR(cz, cpm); const char* cB = PG8_BPTR(cz, cpn);
;     PG8_STAGE(PG8_SB(0, 0), cB, voffB); PG8_STAGE(PG8_SB(0, 1), cB + hstepB, voffB); PG8_STAGE(PG8_SA(0, 0), cA, voffA); PG8_STAGE(PG8_SA(0, 1), cA + hstepA, voffA);
;     if (wr == 1) PG8_BAR;
;     PG8_WAIT_V(2); PG8_BAR;
;     PG8_STAGE(PG8_SB(1, 0), cB + kstep, voffB); PG8_STAGE(PG8_SA(1, 0), cA + kstep, voffA); PG8_STAGE(PG8_SB(1, 1), cB + hstepB + kstep, voffB);
;     __device__ __forceinline__ void preload(f32x4 (&acc)[2][2][4][2], int pm, int pn, int z, int wr, int wc, int fr, int fq) const {
;         const int row0 = pm * BM + wr * 64 + fr, col0 = pn * BM + wc * 32 + 8 * fq;
; #pragma unroll
;         for (int ai = 0; ai < 2; ++ai)
; #pragma unroll
;             for (int m = 0; m < 4; ++m) { const size_t off = (size_t)(row0 + ai * HALF + m * 16) * DM + col0;
; #pragma unroll
;                 for (int bj = 0; bj < 2; ++bj)
; #pragma unroll
;                     for (int n = 0; n < 2; ++n) acc[ai][bj][m][n] = *(const f32x4*)(xin + off + bj * HALF + 4 * n); }
	v_ashrrev_i32_e32 v7, 31, v6
	v_ashrrev_i32_e32 v3, 31, v2
	v_lshlrev_b64 v[4:5], 13, v[0:1]
	v_lshlrev_b64 v[6:7], 13, v[6:7]
	v_lshl_add_u64 v[4:5], s[56:57], 0, v[4:5]
	v_lshlrev_b64 v[2:3], 2, v[2:3]
	v_lshl_add_u64 v[6:7], s[56:57], 0, v[6:7]
	v_lshl_add_u64 v[4:5], v[4:5], 0, v[2:3]
	v_lshl_add_u64 v[6:7], v[6:7], 0, v[2:3]
	global_load_dwordx4 v[116:119], v[4:5], off offset:16
	global_load_dwordx4 v[124:127], v[4:5], off
	global_load_dwordx4 v[112:115], v[4:5], off offset:528
	global_load_dwordx4 v[120:123], v[4:5], off offset:512
	global_load_dwordx4 v[96:99], v[6:7], off offset:16
	global_load_dwordx4 v[104:107], v[6:7], off
	global_load_dwordx4 v[100:103], v[6:7], off offset:528
	global_load_dwordx4 v[108:111], v[6:7], off offset:512
	v_or_b32_e32 v6, 32, v0
	v_or_b32_e32 v0, 48, v0
	v_ashrrev_i32_e32 v7, 31, v6
	v_ashrrev_i32_e32 v1, 31, v0
	v_lshlrev_b64 v[6:7], 13, v[6:7]
	v_lshlrev_b64 v[0:1], 13, v[0:1]
	v_lshl_add_u64 v[6:7], s[56:57], 0, v[6:7]
	v_lshl_add_u64 v[0:1], s[56:57], 0, v[0:1]
	s_mov_b32 s6, 0x100000
	v_lshl_add_u64 v[6:7], v[6:7], 0, v[2:3]
	v_lshl_add_u64 v[0:1], v[0:1], 0, v[2:3]
	v_add_co_u32_e32 v2, vcc, s6, v4
	s_mov_b64 s[10:11], 0x100000
	s_nop 0
	v_addc_co_u32_e32 v3, vcc, 0, v5, vcc
	s_mov_b32 s6, 0x120000
	global_load_dwordx4 v[80:83], v[6:7], off offset:16
	global_load_dwordx4 v[88:91], v[6:7], off
	global_load_dwordx4 v[84:87], v[6:7], off offset:528
	global_load_dwordx4 v[92:95], v[6:7], off offset:512
	global_load_dwordx4 v[64:67], v[0:1], off offset:16
	global_load_dwordx4 v[72:75], v[0:1], off
	global_load_dwordx4 v[68:71], v[0:1], off offset:528
	global_load_dwordx4 v[76:79], v[0:1], off offset:512
	v_lshl_add_u64 v[0:1], v[4:5], 0, s[10:11]
	global_load_dwordx4 v[52:55], v[2:3], off
	global_load_dwordx4 v[48:51], v[0:1], off offset:528
	global_load_dwordx4 v[56:59], v[0:1], off offset:16
	global_load_dwordx4 v[60:63], v[0:1], off offset:512
	v_add_co_u32_e32 v2, vcc, s6, v4
	s_mov_b64 s[10:11], 0x120000
	s_nop 0
	v_addc_co_u32_e32 v3, vcc, 0, v5, vcc
	s_mov_b32 s6, 0x140000
	v_lshl_add_u64 v[0:1], v[4:5], 0, s[10:11]
	global_load_dwordx4 v[40:43], v[2:3], off
	global_load_dwordx4 v[36:39], v[0:1], off offset:528
	global_load_dwordx4 v[32:35], v[0:1], off offset:16
	global_load_dwordx4 v[44:47], v[0:1], off offset:512
	s_mov_b64 s[10:11], 0x140000
	v_add_co_u32_e32 v2, vcc, s6, v4
	v_lshl_add_u64 v[0:1], v[4:5], 0, s[10:11]
	s_nop 0
	v_addc_co_u32_e32 v3, vcc, 0, v5, vcc
	s_mov_b32 s6, 0x160000
	v_readlane_b32 s9, v239, 22
	s_lshl_b32 s2, s2, 10
	global_load_dwordx4 v[20:23], v[2:3], off
	global_load_dwordx4 v[24:27], v[0:1], off offset:528
	global_load_dwordx4 v[16:19], v[0:1], off offset:16
	global_load_dwordx4 v[28:31], v[0:1], off offset:512
	v_add_co_u32_e32 v0, vcc, s6, v4
	s_mul_i32 s6, s9, 0x2c0000
	s_add_u32 s88, s60, s6
	s_mul_hi_i32 s6, s9, 0x2c0000
	s_mov_b64 s[10:11], 0x160000
	s_addc_u32 s89, s61, s6
	s_add_i32 s6, s2, 0
	v_lshl_add_u64 v[12:13], v[4:5], 0, s[10:11]
	v_addc_co_u32_e32 v1, vcc, 0, v5, vcc
	s_add_i32 m0, s6, 0x10000
	global_load_dwordx4 v[4:7], v[0:1], off
	global_load_dwordx4 v[8:11], v[12:13], off offset:528
	s_nop 0
	global_load_dwordx4 v[0:3], v[12:13], off offset:16
	s_nop 0
	global_load_dwordx4 v[12:15], v[12:13], off offset:512
	v_mov_b32_e32 v129, v179
	global_load_lds_dwordx4 v178, s[88:89]
	s_add_i32 m0, s6, 0x12000
	s_add_u32 s10, s88, 0x160000
	global_load_lds_dwordx4 v128, s[88:89]
	s_addc_u32 s11, s89, 0
	s_add_i32 m0, s6, 0x14000
	v_mov_b32_e32 v133, v179
	global_load_lds_dwordx4 v178, s[10:11]
	s_add_i32 m0, s6, 0x16000
	v_mov_b32_e32 v131, v179
	global_load_lds_dwordx4 v128, s[10:11]
	v_readlane_b32 s10, v239, 28
	s_mul_i32 s9, s10, 0x2c0000
	s_add_u32 s46, s62, s9
	s_mul_hi_i32 s9, s10, 0x2c0000
	s_addc_u32 s47, s63, s9
	s_add_i32 s9, s6, 0x2000
	s_mov_b32 m0, s6
	s_add_u32 s16, s46, 0x160000
	v_readlane_b32 s11, v239, 29
	global_load_lds_dwordx4 v132, s[46:47]
	s_mov_b32 m0, s9
	s_addc_u32 s17, s47, 0
	s_add_i32 s10, s6, 0x4000
	global_load_lds_dwordx4 v130, s[46:47]
	s_mov_b32 m0, s10
	s_add_i32 s11, s6, 0x6000
	global_load_lds_dwordx4 v132, s[16:17]
	s_mov_b32 m0, s11
	s_cmp_eq_u32 s22, 1
	global_load_lds_dwordx4 v130, s[16:17]
	v_lshl_add_u64 v[140:141], s[88:89], 0, v[178:179]
	v_lshl_add_u64 v[138:139], s[88:89], 0, v[128:129]
	v_lshl_add_u64 v[134:135], s[46:47], 0, v[132:133]
	s_cselect_b64 s[66:67], -1, 0
	s_cmp_lg_u32 s22, 1
	v_lshl_add_u64 v[136:137], s[46:47], 0, v[130:131]
	s_cbranch_scc1 .LBB0_92
	s_barrier

; #define PG8_WAIT_V(n) asm volatile("s_waitcnt vmcnt(" #n ")" ::: "memory")
; #define PG8_BAR __builtin_amdgcn_s_barrier()
; template <class Epi>
; __device__ __forceinline__ void gemm_phase(LAS unsigned char* lds, const GemmD g, const Epi& E, int G, int c) {
;     ...
;     PG8_WAIT_V(0);
;     PG8_BAR;
; __global__ void __launch_bounds__(512, 2) mega_fwd(Params p_) {
;     ...
;             if (layer == 0) { prep_a(pp, 1, scr, gw, NGW, lane, c * 512 + tid, G * 512); __syncthreads(); }
.LBB0_148:
	s_waitcnt vmcnt(0)
	s_barrier
	s_cmp_eq_u32 s98, 2
	s_cbranch_scc0 .LBB0_149
	s_mov_b32 s98, 0
	s_branch .LBB0_191

; __device__ __forceinline__ void prep_a(CParams* pp, int ly, LAS float* scr, int gw, int NGW, int lane, int gtid, int gthreads) {
;     ...
;     for (int e = gtid; e < M_TOK * 4; e += gthreads) ysq[e] = 0.f;
;     for (int e = gtid; e < M_TOK; e += gthreads) rsb[e] = 0.f;
; __global__ void __launch_bounds__(512, 2) mega_fwd(Params p_) {
;     ...
;             if (layer == 0) { prep_a(pp, 1, scr, gw, NGW, lane, c * 512 + tid, G * 512); __syncthreads(); }
.LBB0_190:
	s_or_b64 exec, exec, s[4:5]
	s_waitcnt vmcnt(0) lgkmcnt(0)
	s_barrier
	s_cmp_eq_u32 s98, 1
	s_cbranch_scc0 .LBB0_191
	s_mov_b32 s98, 2
	s_branch .LBB0_81

; #define LAS __attribute__((address_space(3)))
; __global__ void __launch_bounds__(512, 2) mega_fwd(Params p_) {
;     ...
;         case 6: {
;             {
;             GemmD g{}; g.A = Mg; g.Bt = WoutT; g.lda = DM; g.ldb = DM; g.K = DM; g.nM = 64; g.nN = 8; g.nZ = 1; g.zdiv = 1;
;             EpiRes E{xcur, outp, (bf16_t*)(ws + WS_XBF), rsb, (LAS float*)(lds + RED_OFF)}; gemm_phase(lds, g, E, G, c);
;             }
;             {
;             const float* wg = pp->in[16] + (size_t)layer * DM * DFF; const float* wu = pp->in[17] + (size_t)layer * DM * DFF; const float* wd = pp->in[18] + (size_t)layer * DFF * DM;
;             constexpr int I_GU = 32 * 352, I_D = 88 * 64;
;             for (int it = gw; it < I_GU + I_D; it += NGW) {
;                 int r = it;
;                 if (r < I_GU) { const int kb = r / 352, nb = r % 352; const int tile = nb >> 3, w = nb & 7; transpose_item(w < 4 ? wg : wu, DFF, (tile * 4 + (w & 3)) * 32, WguT, DM, nb * 32, kb * 64, scr, lane, pp->in[15] + layer * DM); continue; }
;                 r -= I_GU;
;                 { const int kb = r / 64, nb = r % 64; transpose_item(wd, DM, nb * 32, WdT, DFF, nb * 32, kb * 64, scr, lane, nullptr); }
;             }
;             for (int e = c * 512 + tid; e < M_TOK; e += G * 512) rsa[e] = 0.f;
;             __syncthreads();
;             }
.LBB0_210:
	s_andn2_b64 vcc, exec, s[4:5]
	s_cbranch_vccnz .LBB0_255
	v_readlane_b32 s4, v240, 59
	v_mov_b32_e32 v0, v176
	v_readlane_b32 s5, v240, 60
	s_andn2_b64 vcc, exec, s[4:5]
	v_readfirstlane_b32 s19, v0
	s_cmp_eq_u32 s98, 2
	s_cbranch_scc1 .Lsw6_second
	s_bitcmp1_b32 s53, 3
	s_cbranch_scc0 .Lsw6_normal
	s_mov_b32 s98, 1
	s_branch .LBB0_235

; #define LAS __attribute__((address_space(3)))
; template <class Epi>
; __device__ __forceinline__ void gemm_phase(LAS unsigned char* lds, const GemmD g, const Epi& E, int G, int c) {
;     int tid_ = threadIdx.x; asm volatile("" : "+v"(tid_));
;     const int tid = tid_, wid = __builtin_amdgcn_readfirstlane(tid >> 6), lane = tid & 63, wr = wid >> 2, wc = wid & 3, fr = lane & 15, fq = lane >> 4;
;     const int K = g.K, nt = K / BK;
;     unsigned voffA[2], voffB[2];
; #pragma unroll
;     for (int i = 0; i < 2; ++i) { int R, C; stage_rc(tid * 16 + i * 8192, R, C); const int Rb = Epi::PERM ? ((R & ~31) + perm32(R & 31)) : R;
;         voffA[i] = (unsigned)(R * g.lda + C) * 2u; voffB[i] = (unsigned)(Rb * g.ldb + C) * 2u; }
;     __device__ __forceinline__ void preload(f32x4 (&acc)[2][2][4][2], int pm, int pn, int z, int wr, int wc, int fr, int fq) const {
;         const int row0 = pm * BM + wr * 64 + fr, col0 = pn * BM + wc * 32 + 8 * fq;
; #pragma unroll
;         for (int ai = 0; ai < 2; ++ai)
; #pragma unroll
;             for (int m = 0; m < 4; ++m) { const size_t off = (size_t)(row0 + ai * HALF + m * 16) * DM + col0;
; #pragma unroll
;                 for (int bj = 0; bj < 2; ++bj)
; #pragma unroll
;                     for (int n = 0; n < 2; ++n) acc[ai][bj][m][n] = *(const f32x4*)(xin + off + bj * HALF + 4 * n); }
.Lsw6_gemm:
	s_waitcnt lgkmcnt(0)
	v_lshlrev_b32_e32 v1, 4, v0
	v_add_u32_e32 v2, 0x2000, v1
	v_ashrrev_i32_e32 v3, 31, v2
	v_lshrrev_b32_e32 v3, 22, v3
	v_add_u32_e32 v3, v2, v3
	v_ashrrev_i32_e32 v145, 10, v3
	v_mul_i32_i24_e32 v3, 0x400, v145
	v_sub_u32_e32 v2, v2, v3
	v_lshrrev_b32_e32 v3, 4, v2
	v_bitop3_b32 v2, v3, v2, 32 bitop3:0x6c
	v_ashrrev_i32_e32 v3, 31, v2
	v_lshrrev_b32_e32 v3, 26, v3
	v_add_u32_e32 v3, v2, v3
	v_lshlrev_b32_e32 v4, 3, v145
	v_ashrrev_i32_e32 v146, 6, v3
	v_and_b32_e32 v4, -16, v4
	v_add_u32_e32 v4, v146, v4
	v_and_b32_e32 v5, 3, v146
	s_mov_b32 s6, 0xfffe0
	v_lshrrev_b32_e32 v6, 2, v4
	v_lshlrev_b32_e32 v7, 1, v4
	v_and_b32_e32 v3, 0xc0, v3
	v_and_or_b32 v5, v4, s6, v5
	v_and_b32_e32 v6, 4, v6
	v_and_b32_e32 v7, 24, v7
	v_sub_u32_e32 v2, v2, v3
	v_or3_b32 v5, v5, v6, v7
	v_lshlrev_b32_e32 v6, 5, v145
	v_ashrrev_i16_sdwa v2, v200, sext(v2) dst_sel:DWORD dst_unused:UNUSED_PAD src0_sel:DWORD src1_sel:BYTE_0
	v_and_b32_e32 v6, 32, v6
	v_bfe_i32 v149, v2, 0, 16
	v_add_lshl_u32 v2, v6, v149, 1
	v_lshl_add_u32 v128, v5, 12, v2
	v_lshl_add_u32 v130, v4, 12, v2
	v_bfe_i32 v2, v0, 27, 1
	v_lshrrev_b32_e32 v2, 22, v2
	v_add_u32_e32 v2, v1, v2
	v_and_b32_e32 v2, 0xfffffc00, v2
	v_sub_u32_e32 v1, v1, v2
	v_lshrrev_b32_e32 v2, 4, v1
	v_ashrrev_i32_e32 v3, 31, v0
	v_bitop3_b32 v1, v2, v1, 32 bitop3:0x6c
	v_lshrrev_b32_e32 v3, 26, v3
	v_bfe_u32 v147, v0, 4, 2
	v_and_b32_e32 v148, 15, v0
	v_ashrrev_i32_e32 v2, 31, v1
	v_add_u32_e32 v0, v0, v3
	v_lshrrev_b32_e32 v2, 26, v2
	v_ashrrev_i32_e32 v151, 6, v0
	v_add_u32_e32 v2, v1, v2
	v_lshlrev_b32_e32 v0, 3, v151
	v_ashrrev_i32_e32 v150, 6, v2
	v_and_b32_e32 v0, -16, v0
	v_add_u32_e32 v0, v150, v0
	v_and_b32_e32 v3, 3, v150
	v_lshrrev_b32_e32 v4, 2, v0
	v_lshlrev_b32_e32 v5, 1, v0
	v_and_b32_e32 v2, 0xc0, v2
	v_and_or_b32 v3, v0, s6, v3
	v_and_b32_e32 v4, 4, v4
	v_and_b32_e32 v5, 24, v5
	v_sub_u32_e32 v1, v1, v2
	s_ashr_i32 s22, s19, 8
	v_or3_b32 v3, v3, v4, v5
	v_lshlrev_b32_e32 v4, 5, v151
	v_ashrrev_i16_sdwa v1, v200, sext(v1) dst_sel:DWORD dst_unused:UNUSED_PAD src0_sel:DWORD src1_sel:BYTE_0
	s_ashr_i32 s2, s19, 6
	s_lshl_b32 s23, s22, 6
	v_and_b32_e32 v4, 32, v4
	v_bfe_i32 v152, v1, 0, 16
	v_readlane_b32 s6, v239, 21
	s_and_b32 s4, s2, 3
	v_add_lshl_u32 v1, v4, v152, 1
	s_add_i32 s6, s6, s23
	s_lshl_b32 s5, s4, 5
	v_lshl_add_u32 v132, v0, 12, v1
	v_or_b32_e32 v0, s6, v148
	v_readlane_b32 s6, v239, 23
	v_lshlrev_b32_e32 v144, 3, v147
	s_or_b32 s6, s6, s5
	v_or_b32_e32 v6, 16, v0
	v_lshl_add_u32 v178, v3, 12, v1
	v_or_b32_e32 v2, s6, v144
	v_ashrrev_i32_e32 v1, 31, v0
	v_readlane_b32 s10, v238, 51
	v_ashrrev_i32_e32 v7, 31, v6
	v_ashrrev_i32_e32 v3, 31, v2
	v_lshlrev_b64 v[4:5], 13, v[0:1]
	v_readlane_b32 s11, v238, 52
	v_lshlrev_b64 v[6:7], 13, v[6:7]
	v_lshlrev_b64 v[2:3], 2, v[2:3]
	v_lshl_add_u64 v[4:5], s[10:11], 0, v[4:5]
	v_lshl_add_u64 v[6:7], s[10:11], 0, v[6:7]
	v_lshl_add_u64 v[4:5], v[4:5], 0, v[2:3]
	v_lshl_add_u64 v[6:7], v[6:7], 0, v[2:3]
	global_load_dwordx4 v[120:123], v[4:5], off offset:16
	global_load_dwordx4 v[124:127], v[4:5], off
	global_load_dwordx4 v[112:115], v[4:5], off offset:528
	global_load_dwordx4 v[116:119], v[4:5], off offset:512
	global_load_dwordx4 v[104:107], v[6:7], off offset:16
	global_load_dwordx4 v[108:111], v[6:7], off
	global_load_dwordx4 v[96:99], v[6:7], off offset:528
	global_load_dwordx4 v[100:103], v[6:7], off offset:512
	v_or_b32_e32 v6, 32, v0
	v_or_b32_e32 v0, 48, v0
	v_ashrrev_i32_e32 v7, 31, v6
	v_ashrrev_i32_e32 v1, 31, v0
	v_lshlrev_b64 v[6:7], 13, v[6:7]
; #define PG8_STAGE(bufoff, gbase, voff) do { _Pragma("unroll") for (int _i = 0; _i < 2; ++_i) \
;         __builtin_amdgcn_global_load_lds((const unsigned*)((const char*)(gbase) + (voff)[_i]), (LAS unsigned*)(lds + (bufoff) + ldsw + _i * 8192), 16, 0, 0); } while (0)
; #define PG8_BAR __builtin_amdgcn_s_barrier()
; template <class Epi>
; __device__ __forceinline__ void gemm_phase(LAS unsigned char* lds, const GemmD g, const Epi& E, int G, int c) {
;     ...
;     const char* cA = PG8_APTR(cz, cpm); const char* cB = PG8_BPTR(cz, cpn);
;     PG8_STAGE(PG8_SB(0, 0), cB, voffB); PG8_STAGE(PG8_SB(0, 1), cB + hstepB, voffB); PG8_STAGE(PG8_SA(0, 0), cA, voffA); PG8_STAGE(PG8_SA(0, 1), cA + hstepA, voffA);
;     if (wr == 1) PG8_BAR;
;     __device__ __forceinline__ void preload(f32x4 (&acc)[2][2][4][2], int pm, int pn, int z, int wr, int wc, int fr, int fq) const {
;         const int row0 = pm * BM + wr * 64 + fr, col0 = pn * BM + wc * 32 + 8 * fq;
; #pragma unroll
;         for (int ai = 0; ai < 2; ++ai)
; #pragma unroll
;             for (int m = 0; m < 4; ++m) { const size_t off = (size_t)(row0 + ai * HALF + m * 16) * DM + col0;
; #pragma unroll
;                 for (int bj = 0; bj < 2; ++bj)
; #pragma unroll
;                     for (int n = 0; n < 2; ++n) acc[ai][bj][m][n] = *(const f32x4*)(xin + off + bj * HALF + 4 * n); }
;     }
	v_lshlrev_b64 v[0:1], 13, v[0:1]
	v_lshl_add_u64 v[6:7], s[10:11], 0, v[6:7]
	v_lshl_add_u64 v[0:1], s[10:11], 0, v[0:1]
	s_mov_b32 s6, 0x100000
	v_lshl_add_u64 v[6:7], v[6:7], 0, v[2:3]
	v_lshl_add_u64 v[0:1], v[0:1], 0, v[2:3]
	v_add_co_u32_e32 v2, vcc, s6, v4
	s_mov_b64 s[10:11], 0x100000
	s_nop 0
	v_addc_co_u32_e32 v3, vcc, 0, v5, vcc
	s_mov_b32 s6, 0x120000
	global_load_dwordx4 v[88:91], v[6:7], off offset:16
	global_load_dwordx4 v[92:95], v[6:7], off
	global_load_dwordx4 v[80:83], v[6:7], off offset:528
	global_load_dwordx4 v[84:87], v[6:7], off offset:512
	global_load_dwordx4 v[72:75], v[0:1], off offset:16
	global_load_dwordx4 v[76:79], v[0:1], off
	global_load_dwordx4 v[64:67], v[0:1], off offset:528
	global_load_dwordx4 v[68:71], v[0:1], off offset:512
	v_lshl_add_u64 v[0:1], v[4:5], 0, s[10:11]
	global_load_dwordx4 v[56:59], v[2:3], off
	global_load_dwordx4 v[48:51], v[0:1], off offset:528
	global_load_dwordx4 v[60:63], v[0:1], off offset:16
	global_load_dwordx4 v[52:55], v[0:1], off offset:512
	s_mov_b64 s[10:11], 0x120000
	v_add_co_u32_e32 v2, vcc, s6, v4
	v_lshl_add_u64 v[0:1], v[4:5], 0, s[10:11]
	s_nop 0
	v_addc_co_u32_e32 v3, vcc, 0, v5, vcc
	s_mov_b64 s[10:11], 0x140000
	global_load_dwordx4 v[40:43], v[2:3], off
	global_load_dwordx4 v[32:35], v[0:1], off offset:528
	global_load_dwordx4 v[36:39], v[0:1], off offset:16
	global_load_dwordx4 v[44:47], v[0:1], off offset:512
	v_lshl_add_u64 v[0:1], v[4:5], 0, s[10:11]
	s_mov_b32 s6, 0x140000
	s_mov_b64 s[10:11], 0x160000
	s_lshl_b32 s2, s2, 10
	v_add_co_u32_e32 v2, vcc, s6, v4
	v_lshl_add_u64 v[6:7], v[4:5], 0, s[10:11]
	v_readlane_b32 s10, v239, 19
	v_readlane_b32 s16, v238, 55
	v_addc_co_u32_e32 v3, vcc, 0, v5, vcc
	s_mov_b32 s6, 0x160000
	v_readlane_b32 s11, v239, 20
	v_readlane_b32 s17, v238, 56
	s_add_u32 s84, s16, s10
	global_load_dwordx4 v[28:31], v[2:3], off
	global_load_dwordx4 v[16:19], v[0:1], off offset:528
	global_load_dwordx4 v[24:27], v[0:1], off offset:16
	global_load_dwordx4 v[20:23], v[0:1], off offset:512
	v_add_co_u32_e32 v0, vcc, s6, v4
	s_addc_u32 s85, s17, s11
	s_add_i32 s6, s2, 0
	v_addc_co_u32_e32 v1, vcc, 0, v5, vcc
	s_add_i32 m0, s6, 0x10000
	global_load_dwordx4 v[12:15], v[0:1], off
	s_nop 0
	global_load_dwordx4 v[0:3], v[6:7], off offset:528
	global_load_dwordx4 v[8:11], v[6:7], off offset:16
	s_nop 0
	global_load_dwordx4 v[4:7], v[6:7], off offset:512
	v_mov_b32_e32 v129, v179
	global_load_lds_dwordx4 v178, s[84:85]
	s_add_i32 m0, s6, 0x12000
	s_add_u32 s10, s84, 0x80000
	global_load_lds_dwordx4 v128, s[84:85]
	s_addc_u32 s11, s85, 0
	s_add_i32 m0, s6, 0x14000
	v_mov_b32_e32 v133, v179
	global_load_lds_dwordx4 v178, s[10:11]
	s_add_i32 m0, s6, 0x16000
	v_mov_b32_e32 v131, v179
	global_load_lds_dwordx4 v128, s[10:11]
	v_readlane_b32 s10, v239, 30
	v_readlane_b32 s11, v239, 31
	s_add_u32 s86, s14, s10
	s_addc_u32 s87, s15, s11
	s_add_i32 s9, s6, 0x2000
	s_mov_b32 m0, s6
	s_add_u32 s16, s86, 0x80000
	global_load_lds_dwordx4 v132, s[86:87]
	s_mov_b32 m0, s9
	s_addc_u32 s17, s87, 0
	s_add_i32 s10, s6, 0x4000
	global_load_lds_dwordx4 v130, s[86:87]
	s_mov_b32 m0, s10
	s_add_i32 s11, s6, 0x6000
	global_load_lds_dwordx4 v132, s[16:17]
	s_mov_b32 m0, s11
	s_cmp_eq_u32 s22, 1
	global_load_lds_dwordx4 v130, s[16:17]
	v_lshl_add_u64 v[140:141], s[84:85], 0, v[178:179]
	v_lshl_add_u64 v[138:139], s[84:85], 0, v[128:129]
	v_lshl_add_u64 v[134:135], s[86:87], 0, v[132:133]
	s_cselect_b64 s[44:45], -1, 0
	s_cmp_lg_u32 s22, 1
	v_lshl_add_u64 v[136:137], s[86:87], 0, v[130:131]
	s_cbranch_scc1 .LBB0_214
	s_barrier

; #define PG8_WAIT_V(n) asm volatile("s_waitcnt vmcnt(" #n ")" ::: "memory")
; #define PG8_BAR __builtin_amdgcn_s_barrier()
; template <class Epi>
; __device__ __forceinline__ void gemm_phase(LAS unsigned char* lds, const GemmD g, const Epi& E, int G, int c) {
;     ...
;     PG8_WAIT_V(0);
;     PG8_BAR;
.LBB0_339:
	s_mov_b32 s98, 0
	s_mov_b32 s99, 0
	s_waitcnt vmcnt(0)
	s_barrier
